# static s_setprio 1 for waves 4-7 during the token-mixing (attention) phase
# baseline (speedup 1.0000x reference)
; __device__ __forceinline__ void mix_phase(const Args& a, LAS unsigned char* lds, int l, int tid_in, int G) {
;     ...
;     const float lam = LAM[l], post_scale = LAM[4 + l];
;     const float* gsub = a.in[I_SUBLN] + l * 128;
;     const int n_ctxd = last ? 0 : 64, n_ctxs = last ? 0 : 32, n_g = last ? 512 : 576;
;     const int e0 = 512, e1 = e0 + 256, e2 = e1 + n_ctxd, e3 = e2 + n_ctxs, e4 = e3 + n_g;
;     for (int u = blockIdx.x; u < e4; u += G) {
;         int tid = tid_in; asm volatile("" : "+v"(tid));
;         if (u < e3) {
.LBB0_100:
	s_and_b64 vcc, exec, s[0:1]
	s_cbranch_vccz .LBB0_181
	s_and_b64 s[0:1], s[8:9], exec
	s_movk_i32 s0, 0x500
	s_cselect_b32 s12, s0, 0x5a0
	s_cmp_ge_i32 s2, s12
	s_cbranch_scc1 .LBB0_181
	s_ashr_i32 s19, s18, 31
	s_lshl_b64 s[0:1], s[18:19], 2
	s_mov_b64 s[10:11], s[8:9]
	v_readlane_b32 s8, v252, 25
	v_readlane_b32 s9, v252, 26
	s_add_u32 s0, s8, s0
	s_addc_u32 s1, s9, s1
	global_load_dword v159, v1, s[0:1]
	global_load_dword v172, v1, s[0:1] offset:16
	v_writelane_b32 v255, s40, 15
	s_lshl_b32 s0, s18, 7
	s_ashr_i32 s1, s0, 31
	v_writelane_b32 v255, s41, 16
	v_readlane_b32 s40, v252, 0
	s_lshl_b64 s[0:1], s[0:1], 2
	v_readlane_b32 s42, v252, 2
	v_readlane_b32 s43, v252, 3
	s_add_u32 s30, s42, s0
	s_addc_u32 s31, s43, s1
	s_and_b64 s[0:1], s[10:11], exec
	s_movk_i32 s0, 0x300
	s_mov_b32 s8, s18
	s_cselect_b32 s13, s0, 0x340
	s_movk_i32 s0, 0x360
	s_mov_b32 s33, 0x800000
	s_cselect_b32 s18, 0x300, s0
	s_mov_b32 s64, s8
	s_lshl_b32 s19, s8, 2
	s_mov_b32 s22, s2
	v_readlane_b32 s41, v252, 1
	v_readlane_b32 s44, v252, 4
	v_readlane_b32 s45, v252, 5
	v_readlane_b32 s46, v252, 6
	v_readlane_b32 s47, v252, 7
	v_readfirstlane_b32 s0, v158
	s_nop 3
	s_lshr_b32 s0, s0, 8
	s_cmp_eq_u32 s0, 0
	s_cbranch_scc1 .Lmix_prio_done
	s_setprio 1
.Lmix_prio_done:
	s_branch .LBB0_106

; __device__ __forceinline__ void mix_phase(const Args& a, LAS unsigned char* lds, int l, int tid_in, int G) {
;     ...
;     for (int u = blockIdx.x; u < e4; u += G) {
;         int tid = tid_in; asm volatile("" : "+v"(tid));
;         if (u < e3) {
;             const bool is_swa = (u >= e0 && u < e1) || (u >= e2);
;             const bool is_ctx = (u >= e1);
;             int b, hh, qb, row0;
;             if (u < e0) {
;                 const int v = u, x = v & 7, slot = (v >> 3) & 31, rnd = v >> 8, P = x * 4 + rnd * 2 + (slot >> 4);
;                 b = P >> 2; hh = P & 3; qb = slot & 15; row0 = b * SEQ + 128 * qb; }
;             else if (u < e1) { const int v = u - e0, x = v & 7, slot = (v >> 3) & 31, P = x * 2 + (slot >> 4); b = P >> 1; hh = P & 1; qb = slot & 15; row0 = b * SEQ + 128 * qb; }
;             else if (u < e2) { const int v = u - e1; b = v >> 3; hh = (v >> 1) & 3; qb = v & 1; row0 = T_LAT + b * CTXL + 128 * qb; }
;             else { const int v = u - e2; b = v >> 2; hh = (v >> 1) & 1; qb = v & 1; row0 = T_LAT + b * CTXL + 128 * qb; }
;             if (!is_swa) {
;                 attn_unit<2, 128, false>(lds, QB + (size_t)row0 * 512 + hh * 128, 512, KB + (size_t)(b * 4 + hh) * NKEY * 128, VBt + (size_t)(b * 4 + hh) * NKEY * 128,
;                                          is_ctx ? 4 : 36, 0, 0, 0, 0.f, lam, gsub, post_scale, O + (size_t)row0 * DM + 256 + hh * 128, tid);
;             } else {
;                 const int kv = hh;
;                 int lo = 4 + 2 * (qb - 1), hi = 4 + 2 * (qb + 2); if (lo < 4) lo = 4; if (hi > 36) hi = 36;
;                 if (is_ctx) { lo = 0; hi = 0; }
;                 attn_unit<2, 64, true>(lds, QC + (size_t)row0 * 256 + kv * 128, 256, KC + (size_t)(b * 2 + kv) * NKEY * 64, VCt + (size_t)(b * 2 + kv) * NKEY * 64,
;                                        4, lo, hi, 128 * qb, a.in[I_SINK][l * 4 + kv * 2] * LOG2E, a.in[I_SINK][l * 4 + kv * 2 + 1] * LOG2E, nullptr, 0.f, O + (size_t)row0 * DM + 768 + kv * 128, tid);
;             }
;         } else {
;             const int v = u - e3, ch = v >> 2, h = v & 3;
;             gmlp_unit(lds, UV, (const bf16_t*)(ws + WS_WS) + (size_t)(l * 4 + h) * 128 * 128, a.in[I_VGAIN] + (l * 4 + h) * 64, a.in[I_BS] + (l * 4 + h) * 128, ch * 128, h, O, tid);
;         }
;     }
; }
.LBB0_180:
	s_setprio 0
	v_readlane_b32 s22, v254, 35
	v_readlane_b32 s24, v254, 37
	v_readlane_b32 s20, v254, 45
	v_readlane_b32 s40, v255, 15
	v_readlane_b32 s23, v254, 36
	v_readlane_b32 s25, v254, 38
	v_readlane_b32 s21, v254, 46
	v_readlane_b32 s41, v255, 16
	s_mov_b32 s18, s64
